# speedup vs baseline: 1.0054x; 1.0054x over previous
; #define LAS __attribute__((address_space(3)))
; __device__ __forceinline__ void build_rtab(unsigned char* ws, LAS float* rtab, int pm) {
;     int t = threadIdx.x; asm volatile("" : "+v"(t));
;     if (t < 256) { const float* sp = (const float*)(ws + WS_SSQ) + (size_t)(pm * 256 + t) * 32; float a = 0.f;
; #pragma unroll
;         for (int j = 0; j < 8; ++j) { const f32x4 v = *(const f32x4*)(sp + 4 * j); a += (v[0] + v[1]) + (v[2] + v[3]); }
;         rtab[t] = __builtin_amdgcn_rsqf(a * (1.0f / DM) + RMS_EPS); }
.LBB0_68:
	v_readlane_b32 s8, v255, 33
	v_mov_b32_e32 v128, v210
	v_mov_b32_e32 v136, v211
	s_mov_b64 s[6:7], s[94:95]
	v_mov_b32_e32 v129, s8
	ds_read_b32 v129, v129
	s_lshl_b32 s41, s22, 8
	s_waitcnt lgkmcnt(0)
	v_cmp_eq_u32_e32 vcc, s22, v129
	s_cbranch_vccnz .LBB0_74
	s_waitcnt lgkmcnt(0)
	v_mov_b32_e32 v129, v230
	s_movk_i32 s8, 0x100
	s_barrier
	s_nop 0
	v_cmp_gt_i32_e32 vcc, s8, v129
	s_and_saveexec_b64 s[8:9], vcc
	s_cbranch_execz .LBB0_71
	v_add_u32_e32 v130, s41, v129
	v_ashrrev_i32_e32 v131, 31, v130
	v_lshlrev_b64 v[130:131], 7, v[130:131]
	v_lshl_add_u64 v[130:131], s[6:7], 0, v[130:131]
	s_mov_b64 s[74:75], 0x1a400000
	v_lshl_add_u64 v[134:135], v[130:131], 0, s[74:75]
	v_add_co_u32_e32 v130, vcc, 0x1a400000, v130
	v_lshl_add_u32 v129, v129, 2, 0
	s_nop 0
	v_addc_co_u32_e32 v131, vcc, 0, v131, vcc
	flat_load_dwordx4 v[130:133], v[130:131]
	s_nop 0
	flat_load_dwordx4 v[138:141], v[134:135] offset:16
	flat_load_dwordx4 v[178:181], v[134:135] offset:32
	flat_load_dwordx4 v[184:187], v[134:135] offset:48
	v_add_u32_e32 v129, 0x22100, v129
	s_waitcnt vmcnt(0) lgkmcnt(0)
	v_mov_b32_e32 v142, v130
	v_mov_b32_e32 v143, v138
	v_mov_b32_e32 v138, v131
	v_pk_add_f32 v[130:131], v[142:143], v[138:139]
	v_mov_b32_e32 v138, v132
	v_mov_b32_e32 v139, v140
	v_mov_b32_e32 v140, v133
	v_pk_add_f32 v[132:133], v[138:139], v[140:141]
	s_nop 0
	v_pk_add_f32 v[130:131], v[130:131], v[132:133]
	s_nop 0
	v_add_f32_e32 v130, 0, v130
	v_add_f32_e32 v138, v130, v131
	v_mov_b32_e32 v130, v178
	v_mov_b32_e32 v131, v179
	v_mov_b32_e32 v132, v180
	v_mov_b32_e32 v133, v181
	v_mov_b32_e32 v140, v131
	v_mov_b32_e32 v141, v132
	v_mov_b32_e32 v131, v133
	v_pk_add_f32 v[130:131], v[140:141], v[130:131]
	s_nop 0
	v_pk_add_f32 v[140:141], v[130:131], v[130:131] op_sel:[0,1] op_sel_hi:[1,0]
	v_mov_b32_e32 v130, v184
	v_mov_b32_e32 v131, v185
	v_mov_b32_e32 v132, v186
	v_mov_b32_e32 v133, v187
	v_add_f32_e32 v142, v130, v131
	v_add_f32_e32 v144, v132, v133
	flat_load_dwordx4 v[130:133], v[134:135] offset:64
	flat_load_dwordx4 v[178:181], v[134:135] offset:80
	flat_load_dwordx4 v[184:187], v[134:135] offset:96
	s_waitcnt vmcnt(0) lgkmcnt(0)
	v_mov_b32_e32 v139, v130
	v_mov_b32_e32 v141, v131
	v_mov_b32_e32 v143, v132
	v_mov_b32_e32 v145, v133
	v_pk_add_f32 v[130:131], v[138:139], v[140:141]
	v_pk_add_f32 v[132:133], v[142:143], v[144:145]
	s_nop 0
	v_pk_add_f32 v[130:131], v[130:131], v[132:133]
	s_nop 0
	v_pk_add_f32 v[138:139], v[130:131], v[130:131] op_sel:[0,1] op_sel_hi:[1,0]
	v_mov_b32_e32 v130, v178
	v_mov_b32_e32 v131, v179
	v_mov_b32_e32 v132, v180
	v_mov_b32_e32 v133, v181
	flat_load_dwordx4 v[178:181], v[134:135] offset:112
	v_mov_b32_e32 v140, v131
	v_mov_b32_e32 v141, v132
	v_mov_b32_e32 v131, v133
	v_pk_add_f32 v[130:131], v[140:141], v[130:131]
	s_nop 0
	v_pk_add_f32 v[140:141], v[130:131], v[130:131] op_sel:[0,1] op_sel_hi:[1,0]
	v_mov_b32_e32 v130, v184
	v_mov_b32_e32 v131, v185
	v_mov_b32_e32 v132, v186
	v_mov_b32_e32 v133, v187
	v_add_f32_e32 v142, v130, v131
	v_add_f32_e32 v144, v132, v133
	s_waitcnt vmcnt(0) lgkmcnt(0)
	v_mov_b32_e32 v130, v178
	v_mov_b32_e32 v131, v179
	v_mov_b32_e32 v132, v180
	v_mov_b32_e32 v133, v181
	v_mov_b32_e32 v139, v130
	v_mov_b32_e32 v141, v131
	v_mov_b32_e32 v143, v132
	v_mov_b32_e32 v145, v133
	v_pk_add_f32 v[130:131], v[138:139], v[140:141]
	v_pk_add_f32 v[132:133], v[142:143], v[144:145]
	s_nop 0
	v_pk_add_f32 v[130:131], v[130:131], v[132:133]
	s_nop 0
	v_add_f32_e32 v130, v130, v131
	v_fmamk_f32 v130, v130, 0x3a000000, v232
	v_rsq_f32_e32 v130, v130
	ds_write_b32 v129, v130
